# v_g35 + FoX loop: MFMA-to-VALU hazard gap (s_nop 5) filled with next-buffer LDS write address computation; tile-end block reduced
# baseline (speedup 1.0000x reference)
; template <int DK, int MODE> ...
;     ...
;   auto gload = [&](int jt) {
; #pragma unroll
;     for (int i = 0; i < NKL; ++i) {
;       const int id = tid + 256 * i, row = id / KCH, ch = id % KCH;
;       rk[i] = *(const u32x4*)(K + (size_t)(jt * 64 + row) * DK + ch * 8);
;     }
; #pragma unroll
;     for (int i = 0; i < 2; ++i) {
;       const int id = tid + 256 * i, row = id >> 3, ch = id & 7;
;       rv[i] = *(const u32x4*)(Vt + (size_t)row * Skv + jt * 64 + ch * 8);
;     }
;     if (MODE == 1) rf = F[jt * 64 + (tid & 63)];
;   };
;   auto swrite = [&](int buf) {
; #pragma unroll
;     for (int i = 0; i < NKL; ++i) {
;       const int id = tid + 256 * i, row = id / KCH, ch = id % KCH;
;       *(u32x4*)(sK + buf * 64 * LDK + row * LDK + ch * 8) = rk[i];
;     }
; #pragma unroll
;     for (int i = 0; i < 2; ++i) {
;       const int id = tid + 256 * i, row = id >> 3, ch = id & 7;
;       *(u32x4*)(sV + buf * 64 * 72 + row * 72 + ch * 8) = rv[i];
;     }
;     if (MODE == 1) { if (tid < 64) sF[buf * 64 + tid] = Fref - rf; }
;   };
.Lfox_inactive:
	v_lshl_add_u64 v[34:35], v[228:229], 0, s[100:101]
	v_lshl_add_u64 v[36:37], v[230:231], 0, s[100:101]
	global_load_dwordx4 v[82:85], v[34:35], off
	global_load_dwordx4 v[86:89], v[36:37], off
	v_lshl_add_u64 v[34:35], v[142:143], 0, s[24:25]
	v_lshl_add_u64 v[36:37], v[152:153], 0, s[24:25]
	global_load_dwordx4 v[90:93], v[34:35], off
	global_load_dwordx4 v[94:97], v[36:37], off
	v_lshl_add_u64 v[34:35], s[24:25], 1, v[232:233]
	global_load_dword v160, v[34:35], off
	s_xor_b32 s100, s11, 1
	s_mul_i32 s100, s100, 0x2400
	v_add_u32_e32 v248, s100, v222
	v_add_u32_e32 v249, s100, v223
	v_add_u32_e32 v250, s100, v224
	v_add_u32_e32 v251, s100, v225
	s_branch .LBB0_568

; template <int DK, int MODE> ...
;     ...
;         float mx = s0[0];
; #pragma unroll
;         for (int e = 1; e < 16; ++e) mx = fmaxf(mx, s0[e]);
; #pragma unroll
;         for (int e = 0; e < 16; ++e) mx = fmaxf(mx, s1[e]);
;         mx = fmaxf(mx, __shfl_xor(mx, 32));
;         if (__any(mx > m + 8.f)) {
;           const float mnew = fmaxf(m, mx);
;           const float alpha = __builtin_amdgcn_exp2f(m - mnew);
;           m = mnew; lsum *= alpha;
; #pragma unroll
;           for (int e = 0; e < 16; ++e) { o0[e] *= alpha; o1[e] *= alpha; }
;         }
.LBB0_565:
	s_xor_b32 s100, s11, 1
	s_mul_i32 s100, s100, 0x2400
	v_add_u32_e32 v248, s100, v222
	v_add_u32_e32 v249, s100, v223
	v_add_u32_e32 v250, s100, v224
	v_add_u32_e32 v251, s100, v225
	v_max_f32_e32 v164, v50, v51
	v_max3_f32 v164, v164, v52, v53
	v_max3_f32 v164, v164, v54, v55
	v_max3_f32 v164, v164, v56, v57
	v_max3_f32 v164, v164, v58, v59
	v_max3_f32 v164, v164, v60, v61
	v_max3_f32 v164, v164, v62, v63
	v_max3_f32 v164, v164, v64, v65
	v_max3_f32 v164, v164, v34, v35
	v_max3_f32 v164, v164, v36, v37
	v_max3_f32 v164, v164, v38, v39
	v_max3_f32 v164, v164, v40, v41
	v_max3_f32 v164, v164, v42, v43
	v_max3_f32 v164, v164, v44, v45
	v_max3_f32 v164, v164, v46, v47
	v_max3_f32 v164, v164, v48, v49
	ds_bpermute_b32 v165, v151, v164
	s_waitcnt lgkmcnt(0)
	v_max_f32_e32 v164, v164, v165
	v_add_f32_e32 v165, 0x41000000, v163
	v_cmp_gt_f32_e32 vcc, v164, v165
	s_cbranch_vccz .LBB0_567
	v_max_f32_e32 v164, v164, v164
	v_max_f32_e32 v165, v163, v163
	v_max_f32_e32 v165, v165, v164
	v_sub_f32_e32 v163, v163, v165
	v_exp_f32_e32 v164, v163
	v_mov_b32_e32 v163, v165
	v_pk_mul_f32 v[32:33], v[32:33], v[164:165] op_sel_hi:[1,0]
	v_pk_mul_f32 v[30:31], v[30:31], v[164:165] op_sel_hi:[1,0]
	v_pk_mul_f32 v[28:29], v[28:29], v[164:165] op_sel_hi:[1,0]
	v_pk_mul_f32 v[26:27], v[26:27], v[164:165] op_sel_hi:[1,0]
	v_pk_mul_f32 v[24:25], v[24:25], v[164:165] op_sel_hi:[1,0]
	v_pk_mul_f32 v[22:23], v[22:23], v[164:165] op_sel_hi:[1,0]
	v_pk_mul_f32 v[20:21], v[20:21], v[164:165] op_sel_hi:[1,0]
	v_pk_mul_f32 v[18:19], v[18:19], v[164:165] op_sel_hi:[1,0]
	v_pk_mul_f32 v[16:17], v[16:17], v[164:165] op_sel_hi:[1,0]
	v_pk_mul_f32 v[14:15], v[14:15], v[164:165] op_sel_hi:[1,0]
	v_pk_mul_f32 v[12:13], v[12:13], v[164:165] op_sel_hi:[1,0]
	v_pk_mul_f32 v[10:11], v[10:11], v[164:165] op_sel_hi:[1,0]
	v_pk_mul_f32 v[8:9], v[8:9], v[164:165] op_sel_hi:[1,0]
	v_pk_mul_f32 v[6:7], v[6:7], v[164:165] op_sel_hi:[1,0]
	v_pk_mul_f32 v[4:5], v[4:5], v[164:165] op_sel_hi:[1,0]
	v_pk_mul_f32 v[2:3], v[2:3], v[164:165] op_sel_hi:[1,0]
	v_mul_f32_e32 v135, v135, v164

; template <int DK, int MODE> ...
;     ...
;   auto swrite = [&](int buf) {
; #pragma unroll
;     for (int i = 0; i < NKL; ++i) {
;       const int id = tid + 256 * i, row = id / KCH, ch = id % KCH;
;       *(u32x4*)(sK + buf * 64 * LDK + row * LDK + ch * 8) = rk[i];
;     }
; #pragma unroll
;     for (int i = 0; i < 2; ++i) {
;       const int id = tid + 256 * i, row = id >> 3, ch = id & 7;
;       *(u32x4*)(sV + buf * 64 * 72 + row * 72 + ch * 8) = rv[i];
;     }
;     if (MODE == 1) { if (tid < 64) sF[buf * 64 + tid] = Fref - rf; }
;   };
.LBB0_568:
	s_andn2_b64 vcc, exec, s[22:23]
	s_cbranch_vccnz .LBB0_559
	s_xor_b32 s11, s11, 1
	s_waitcnt vmcnt(4)
	ds_write_b128 v248, v[82:85]
	s_waitcnt vmcnt(3)
	ds_write_b128 v249, v[86:89]
	s_waitcnt vmcnt(2)
	ds_write_b128 v250, v[90:93] offset:18432
	s_waitcnt vmcnt(1)
	ds_write_b128 v251, v[94:97] offset:18432
	s_and_saveexec_b64 s[22:23], s[38:39]
	s_cbranch_execz .LBB0_558
	v_lshl_add_u32 v34, s11, 8, v161
	s_waitcnt vmcnt(0)
	v_sub_f32_e32 v35, v133, v160
	ds_write_b32 v34, v35 offset:36864
	s_branch .LBB0_558

; __global__ void __launch_bounds__(256, 2) mega(Params p_unused) {
;   __shared__ __attribute__((aligned(16))) char smem[SMEM_BYTES];
	.amdhsa_kernel _Z4mega6Params
		.amdhsa_group_segment_fixed_size 74752
		.amdhsa_private_segment_fixed_size 0
		.amdhsa_kernarg_size 648
		.amdhsa_user_sgpr_count 2
		.amdhsa_user_sgpr_dispatch_ptr 0
		.amdhsa_user_sgpr_queue_ptr 0
		.amdhsa_user_sgpr_kernarg_segment_ptr 1
		.amdhsa_user_sgpr_dispatch_id 0
		.amdhsa_user_sgpr_kernarg_preload_length 0
		.amdhsa_user_sgpr_kernarg_preload_offset 0
		.amdhsa_user_sgpr_private_segment_size 0
		.amdhsa_uses_dynamic_stack 0
		.amdhsa_enable_private_segment 0
		.amdhsa_system_sgpr_workgroup_id_x 1
		.amdhsa_system_sgpr_workgroup_id_y 0
		.amdhsa_system_sgpr_workgroup_id_z 0
		.amdhsa_system_sgpr_workgroup_info 0
		.amdhsa_system_vgpr_workitem_id 2
		.amdhsa_next_free_vgpr 256
		.amdhsa_next_free_sgpr 102
		.amdhsa_accum_offset 256
		.amdhsa_reserve_vcc 1
		.amdhsa_float_round_mode_32 0
		.amdhsa_float_round_mode_16_64 0
		.amdhsa_float_denorm_mode_32 3
		.amdhsa_float_denorm_mode_16_64 3
		.amdhsa_dx10_clamp 1
		.amdhsa_ieee_mode 1
		.amdhsa_fp16_overflow 0
		.amdhsa_tg_split 0
		.amdhsa_exception_fp_ieee_invalid_op 0
		.amdhsa_exception_fp_denorm_src 0
		.amdhsa_exception_fp_ieee_div_zero 0
		.amdhsa_exception_fp_ieee_overflow 0
		.amdhsa_exception_fp_ieee_underflow 0
		.amdhsa_exception_fp_ieee_inexact 0
		.amdhsa_exception_int_div_zero 0
	.end_amdhsa_kernel

; __global__ void __launch_bounds__(256, 2) mega(Params p_unused) {
;   __shared__ __attribute__((aligned(16))) char smem[SMEM_BYTES];
amdhsa.kernels:
  - .agpr_count:     0
    .args:
      - .offset:         0
        .size:           392
        .value_kind:     by_value
      - .offset:         392
        .size:           4
        .value_kind:     hidden_block_count_x
      - .offset:         396
        .size:           4
        .value_kind:     hidden_block_count_y
      - .offset:         400
        .size:           4
        .value_kind:     hidden_block_count_z
      - .offset:         404
        .size:           2
        .value_kind:     hidden_group_size_x
      - .offset:         406
        .size:           2
        .value_kind:     hidden_group_size_y
      - .offset:         408
        .size:           2
        .value_kind:     hidden_group_size_z
      - .offset:         410
        .size:           2
        .value_kind:     hidden_remainder_x
      - .offset:         412
        .size:           2
        .value_kind:     hidden_remainder_y
      - .offset:         414
        .size:           2
        .value_kind:     hidden_remainder_z
      - .offset:         432
        .size:           8
        .value_kind:     hidden_global_offset_x
      - .offset:         440
        .size:           8
        .value_kind:     hidden_global_offset_y
      - .offset:         448
        .size:           8
        .value_kind:     hidden_global_offset_z
      - .offset:         456
        .size:           2
        .value_kind:     hidden_grid_dims
      - .offset:         480
        .size:           8
        .value_kind:     hidden_multigrid_sync_arg
    .group_segment_fixed_size: 74752
    .kernarg_segment_align: 8
    .kernarg_segment_size: 648
    .language:       OpenCL C
    .language_version:
      - 2
      - 0
    .max_flat_workgroup_size: 256
    .name:           _Z4mega6Params
    .private_segment_fixed_size: 0
    .sgpr_count:     108
    .sgpr_spill_count: 74
    .symbol:         _Z4mega6Params.kd
    .uniform_work_group_size: 1
    .uses_dynamic_stack: false
    .vgpr_count:     256
    .vgpr_spill_count: 0
    .wavefront_size: 64
